# hand-scheduled single-pass 192-key attention core (ALiBi bias folded into MFMA accumulator init, pipelined LDS reads) + XA cache prefetch in one round trip
# speedup vs baseline: 1.0294x; 1.0095x over previous
.LBB0_500:
	s_and_b64 vcc, exec, s[0:1]
	s_cbranch_vccz .LBB0_431
	v_lshlrev_b32_e32 v194, 2, v70
	v_or_b32_e32 v247, 0x80, v67
	v_sub_u32_e32 v247, v247, v194
	v_cvt_f32_u32_e32 v156, v247
	v_mul_f32_e32 v240, 0x40b17218, v157
	v_mul_u32_u24_e32 v252, 0x90, v66
	v_add_u32_e32 v192, v252, v69
	ds_read_b128 v[0:3], v192 offset:0
	ds_read_b128 v[4:7], v192 offset:32
	ds_read_b128 v[8:11], v192 offset:64
	ds_read_b128 v[12:15], v192 offset:96
	ds_read_b128 v[236:239], v192 offset:4608
	ds_read_b128 v[248:251], v192 offset:4640
	ds_read_b128 v[184:187], v192 offset:4672
	ds_read_b128 v[188:191], v192 offset:4704
	v_mul_f32_e64 v241, -v240, v156
	v_lshrrev_b32_e32 v247, 2, v65
	v_and_or_b32 v247, v247, 3, v194
	v_mul_u32_u24_e32 v202, 0xc0, v247
	v_lshlrev_b32_e32 v247, 1, v68
	v_and_b32_e32 v247, 32, v247
	v_lshlrev_b32_e32 v252, 3, v68
	v_and_b32_e32 v252, 24, v252
	v_add3_u32 v202, v202, v247, v252
	v_fmamk_f32 v32, v240, 0x00000000, v241
	v_fmamk_f32 v33, v240, 0x3f800000, v241
	v_fmamk_f32 v34, v240, 0x40000000, v241
	v_fmamk_f32 v35, v240, 0x40400000, v241
	v_fmamk_f32 v36, v240, 0x41000000, v241
	v_fmamk_f32 v37, v240, 0x41100000, v241
	v_fmamk_f32 v38, v240, 0x41200000, v241
	v_fmamk_f32 v39, v240, 0x41300000, v241
	v_fmamk_f32 v40, v240, 0x41800000, v241
	v_fmamk_f32 v41, v240, 0x41880000, v241
	v_fmamk_f32 v42, v240, 0x41900000, v241
	v_fmamk_f32 v43, v240, 0x41980000, v241
	v_fmamk_f32 v44, v240, 0x41c00000, v241
	v_fmamk_f32 v45, v240, 0x41c80000, v241
	v_fmamk_f32 v46, v240, 0x41d00000, v241
	v_fmamk_f32 v47, v240, 0x41d80000, v241
	s_waitcnt lgkmcnt(7)
	s_nop 0
	v_mfma_f32_32x32x16_bf16 v[32:47], v[0:3], v[104:107], v[32:47]
	v_fmamk_f32 v48, v240, 0x42000000, v241
	v_fmamk_f32 v49, v240, 0x42040000, v241
	v_fmamk_f32 v50, v240, 0x42080000, v241
	v_fmamk_f32 v51, v240, 0x420c0000, v241
	v_fmamk_f32 v52, v240, 0x42200000, v241
	s_waitcnt lgkmcnt(6)
	v_mfma_f32_32x32x16_bf16 v[32:47], v[4:7], v[108:111], v[32:47]
	v_fmamk_f32 v53, v240, 0x42240000, v241
	v_fmamk_f32 v54, v240, 0x42280000, v241
	v_fmamk_f32 v55, v240, 0x422c0000, v241
	v_fmamk_f32 v56, v240, 0x42400000, v241
	v_fmamk_f32 v57, v240, 0x42440000, v241
	s_waitcnt lgkmcnt(5)
	v_mfma_f32_32x32x16_bf16 v[32:47], v[8:11], v[112:115], v[32:47]
	v_fmamk_f32 v58, v240, 0x42480000, v241
	v_fmamk_f32 v59, v240, 0x424c0000, v241
	v_fmamk_f32 v60, v240, 0x42600000, v241
	v_fmamk_f32 v61, v240, 0x42640000, v241
	v_fmamk_f32 v62, v240, 0x42680000, v241
	s_waitcnt lgkmcnt(4)
	v_mfma_f32_32x32x16_bf16 v[32:47], v[12:15], v[116:119], v[32:47]
	v_fmamk_f32 v63, v240, 0x426c0000, v241
	ds_read_b128 v[0:3], v192 offset:9216
	ds_read_b128 v[4:7], v192 offset:9248
	ds_read_b128 v[8:11], v192 offset:9280
	ds_read_b128 v[12:15], v192 offset:9312
	s_waitcnt lgkmcnt(7)
	v_mfma_f32_32x32x16_bf16 v[48:63], v[236:239], v[104:107], v[48:63]
	v_fmamk_f32 v64, v240, 0x42800000, v241
	v_fmamk_f32 v65, v240, 0x42820000, v241
	v_fmamk_f32 v66, v240, 0x42840000, v241
	v_fmamk_f32 v67, v240, 0x42860000, v241
	v_fmamk_f32 v68, v240, 0x42900000, v241
	s_waitcnt lgkmcnt(6)
	v_mfma_f32_32x32x16_bf16 v[48:63], v[248:251], v[108:111], v[48:63]
	v_fmamk_f32 v69, v240, 0x42920000, v241
	v_fmamk_f32 v70, v240, 0x42940000, v241
	v_fmamk_f32 v71, v240, 0x42960000, v241
	v_fmamk_f32 v72, v240, 0x42a00000, v241
	v_fmamk_f32 v73, v240, 0x42a20000, v241
	s_waitcnt lgkmcnt(5)
	v_mfma_f32_32x32x16_bf16 v[48:63], v[184:187], v[112:115], v[48:63]
	v_fmamk_f32 v74, v240, 0x42a40000, v241
	v_fmamk_f32 v75, v240, 0x42a60000, v241
	v_fmamk_f32 v76, v240, 0x42b00000, v241
	v_fmamk_f32 v77, v240, 0x42b20000, v241
	v_fmamk_f32 v78, v240, 0x42b40000, v241
	s_waitcnt lgkmcnt(4)
	v_mfma_f32_32x32x16_bf16 v[48:63], v[188:191], v[116:119], v[48:63]
	v_fmamk_f32 v79, v240, 0x42b60000, v241
	ds_read_b128 v[236:239], v192 offset:13824
	ds_read_b128 v[248:251], v192 offset:13856
	ds_read_b128 v[184:187], v192 offset:13888
	ds_read_b128 v[188:191], v192 offset:13920
	s_waitcnt lgkmcnt(7)
	v_mfma_f32_32x32x16_bf16 v[64:79], v[0:3], v[104:107], v[64:79]
	v_fmamk_f32 v168, v240, 0x42c00000, v241
	v_fmamk_f32 v169, v240, 0x42c20000, v241
	v_fmamk_f32 v170, v240, 0x42c40000, v241
	v_fmamk_f32 v171, v240, 0x42c60000, v241
	v_fmamk_f32 v172, v240, 0x42d00000, v241
	s_waitcnt lgkmcnt(6)
	v_mfma_f32_32x32x16_bf16 v[64:79], v[4:7], v[108:111], v[64:79]
	v_fmamk_f32 v173, v240, 0x42d20000, v241
	v_fmamk_f32 v174, v240, 0x42d40000, v241
	v_fmamk_f32 v175, v240, 0x42d60000, v241
	v_fmamk_f32 v176, v240, 0x42e00000, v241
	v_fmamk_f32 v177, v240, 0x42e20000, v241
	s_waitcnt lgkmcnt(5)
	v_mfma_f32_32x32x16_bf16 v[64:79], v[8:11], v[112:115], v[64:79]
	v_fmamk_f32 v178, v240, 0x42e40000, v241
	v_fmamk_f32 v179, v240, 0x42e60000, v241
	v_fmamk_f32 v180, v240, 0x42f00000, v241
	v_fmamk_f32 v181, v240, 0x42f20000, v241
	v_fmamk_f32 v182, v240, 0x42f40000, v241
	s_waitcnt lgkmcnt(4)
	v_mfma_f32_32x32x16_bf16 v[64:79], v[12:15], v[116:119], v[64:79]
	v_fmamk_f32 v183, v240, 0x42f60000, v241
	ds_read_b128 v[0:3], v192 offset:18432
	ds_read_b128 v[4:7], v192 offset:18464
	ds_read_b128 v[8:11], v192 offset:18496
	ds_read_b128 v[12:15], v192 offset:18528
	s_waitcnt lgkmcnt(7)
	v_mfma_f32_32x32x16_bf16 v[168:183], v[236:239], v[104:107], v[168:183]
	v_subrev_f32_e32 v220, 0x43000000, v156
	v_mul_f32_e64 v220, -|v220|, v240
	v_subrev_f32_e32 v221, 0x43010000, v156
	v_mul_f32_e64 v221, -|v221|, v240
	v_subrev_f32_e32 v222, 0x43020000, v156
	v_mul_f32_e64 v222, -|v222|, v240
	v_subrev_f32_e32 v223, 0x43030000, v156
	v_mul_f32_e64 v223, -|v223|, v240
	v_subrev_f32_e32 v224, 0x43080000, v156
	s_waitcnt lgkmcnt(6)
	v_mfma_f32_32x32x16_bf16 v[168:183], v[248:251], v[108:111], v[168:183]
	v_mul_f32_e64 v224, -|v224|, v240
	v_subrev_f32_e32 v225, 0x43090000, v156
	v_mul_f32_e64 v225, -|v225|, v240
	v_subrev_f32_e32 v226, 0x430a0000, v156
	v_mul_f32_e64 v226, -|v226|, v240
	v_subrev_f32_e32 v227, 0x430b0000, v156
	v_mul_f32_e64 v227, -|v227|, v240
	v_subrev_f32_e32 v228, 0x43100000, v156
	v_mul_f32_e64 v228, -|v228|, v240
	s_waitcnt lgkmcnt(5)
	v_mfma_f32_32x32x16_bf16 v[168:183], v[184:187], v[112:115], v[168:183]
	v_subrev_f32_e32 v229, 0x43110000, v156
	v_mul_f32_e64 v229, -|v229|, v240
	v_subrev_f32_e32 v230, 0x43120000, v156
	v_mul_f32_e64 v230, -|v230|, v240
	v_subrev_f32_e32 v231, 0x43130000, v156
	v_mul_f32_e64 v231, -|v231|, v240
	v_subrev_f32_e32 v232, 0x43180000, v156
	v_mul_f32_e64 v232, -|v232|, v240
	v_subrev_f32_e32 v233, 0x43190000, v156
	s_waitcnt lgkmcnt(4)
	v_mfma_f32_32x32x16_bf16 v[168:183], v[188:191], v[116:119], v[168:183]
	v_mul_f32_e64 v233, -|v233|, v240
	v_subrev_f32_e32 v234, 0x431a0000, v156
	v_mul_f32_e64 v234, -|v234|, v240
	v_subrev_f32_e32 v235, 0x431b0000, v156
	v_mul_f32_e64 v235, -|v235|, v240
	ds_read_b128 v[236:239], v192 offset:23040
	ds_read_b128 v[248:251], v192 offset:23072
	ds_read_b128 v[184:187], v192 offset:23104
	ds_read_b128 v[188:191], v192 offset:23136
	s_waitcnt lgkmcnt(7)
	v_mfma_f32_32x32x16_bf16 v[220:235], v[0:3], v[104:107], v[220:235]
	v_subrev_f32_e32 v16, 0x43200000, v156
	v_mul_f32_e64 v16, -|v16|, v240
	v_subrev_f32_e32 v17, 0x43210000, v156
	v_mul_f32_e64 v17, -|v17|, v240
	v_subrev_f32_e32 v18, 0x43220000, v156
	v_mul_f32_e64 v18, -|v18|, v240
	v_subrev_f32_e32 v19, 0x43230000, v156
	v_mul_f32_e64 v19, -|v19|, v240
	s_waitcnt lgkmcnt(6)
	v_mfma_f32_32x32x16_bf16 v[220:235], v[4:7], v[108:111], v[220:235]
	v_subrev_f32_e32 v20, 0x43280000, v156
	v_mul_f32_e64 v20, -|v20|, v240
	v_subrev_f32_e32 v21, 0x43290000, v156
	v_mul_f32_e64 v21, -|v21|, v240
	v_subrev_f32_e32 v22, 0x432a0000, v156
	v_mul_f32_e64 v22, -|v22|, v240
	v_subrev_f32_e32 v23, 0x432b0000, v156
	v_mul_f32_e64 v23, -|v23|, v240
	s_waitcnt lgkmcnt(5)
	v_mfma_f32_32x32x16_bf16 v[220:235], v[8:11], v[112:115], v[220:235]
	v_subrev_f32_e32 v24, 0x43300000, v156
	v_mul_f32_e64 v24, -|v24|, v240
	v_subrev_f32_e32 v25, 0x43310000, v156
	v_mul_f32_e64 v25, -|v25|, v240
	v_subrev_f32_e32 v26, 0x43320000, v156
	v_mul_f32_e64 v26, -|v26|, v240
	v_subrev_f32_e32 v27, 0x43330000, v156
	v_mul_f32_e64 v27, -|v27|, v240
	s_waitcnt lgkmcnt(4)
	v_mfma_f32_32x32x16_bf16 v[220:235], v[12:15], v[116:119], v[220:235]
	v_subrev_f32_e32 v28, 0x43380000, v156
	v_mul_f32_e64 v28, -|v28|, v240
	v_subrev_f32_e32 v29, 0x43390000, v156
	v_mul_f32_e64 v29, -|v29|, v240
	v_subrev_f32_e32 v30, 0x433a0000, v156
	v_mul_f32_e64 v30, -|v30|, v240
	v_subrev_f32_e32 v31, 0x433b0000, v156
	v_mul_f32_e64 v31, -|v31|, v240
	s_waitcnt lgkmcnt(3)
	s_nop 0
	v_mfma_f32_32x32x16_bf16 v[16:31], v[236:239], v[104:107], v[16:31]
	s_waitcnt lgkmcnt(2)
	v_mfma_f32_32x32x16_bf16 v[16:31], v[248:251], v[108:111], v[16:31]
	s_waitcnt lgkmcnt(1)
	v_mfma_f32_32x32x16_bf16 v[16:31], v[184:187], v[112:115], v[16:31]
	s_waitcnt lgkmcnt(0)
	v_mfma_f32_32x32x16_bf16 v[16:31], v[188:191], v[116:119], v[16:31]
	v_max_f32_e32 v218, v32, v33
	v_max_f32_e32 v219, v34, v35
	v_max_f32_e32 v246, v36, v37
	v_max3_f32 v218, v218, v38, v39
	v_max3_f32 v219, v219, v40, v41
	v_max3_f32 v246, v246, v42, v43
	v_max3_f32 v218, v218, v44, v45
	v_max3_f32 v219, v219, v46, v47
	v_max3_f32 v246, v246, v48, v49
	v_max3_f32 v218, v218, v50, v51
	v_max3_f32 v219, v219, v52, v53
	v_max3_f32 v246, v246, v54, v55
	v_max3_f32 v218, v218, v56, v57
	v_max3_f32 v219, v219, v58, v59
	v_max3_f32 v246, v246, v60, v61
	v_max3_f32 v218, v218, v62, v63
	v_max3_f32 v219, v219, v64, v65
	v_max3_f32 v246, v246, v66, v67
	v_max3_f32 v218, v218, v68, v69
	v_max3_f32 v219, v219, v70, v71
	v_max3_f32 v246, v246, v72, v73
	v_max3_f32 v218, v218, v74, v75
	v_max3_f32 v219, v219, v76, v77
	v_max3_f32 v246, v246, v78, v79
	v_max3_f32 v218, v218, v168, v169
	v_max3_f32 v219, v219, v170, v171
	v_max3_f32 v246, v246, v172, v173
	v_max3_f32 v218, v218, v174, v175
	v_max3_f32 v219, v219, v176, v177
	v_max3_f32 v246, v246, v178, v179
	v_max3_f32 v218, v218, v180, v181
	v_max3_f32 v219, v219, v182, v183
	v_max3_f32 v246, v246, v220, v221
	v_max3_f32 v218, v218, v222, v223
	v_max3_f32 v219, v219, v224, v225
	v_max3_f32 v246, v246, v226, v227
	v_max3_f32 v218, v218, v228, v229
	v_max3_f32 v219, v219, v230, v231
	v_max3_f32 v246, v246, v232, v233
	v_max3_f32 v218, v218, v234, v235
	v_max3_f32 v219, v219, v16, v17
	v_max3_f32 v246, v246, v18, v19
	v_max3_f32 v218, v218, v20, v21
	v_max3_f32 v219, v219, v22, v23
	v_max3_f32 v246, v246, v24, v25
	v_max3_f32 v218, v218, v26, v27
	v_max3_f32 v219, v219, v28, v29
	v_max3_f32 v246, v246, v30, v31
	v_max3_f32 v218, v218, v219, v246
	v_mov_b32_e32 v219, v218
	s_nop 1
	v_permlane32_swap_b32_e32 v218, v219
	v_max_f32_e32 v218, v218, v219
	v_mul_f32_e32 v218, v204, v218
	v_max_f32_e32 v218, v218, v164
	ds_read_b64_tr_b16 v[236:237], v202 offset:27648
	ds_read_b64_tr_b16 v[238:239], v202 offset:29184
	ds_read_b64_tr_b16 v[248:249], v202 offset:27712
	ds_read_b64_tr_b16 v[250:251], v202 offset:29248
	v_fma_f32 v16, v16, v204, -v218
	v_fma_f32 v17, v17, v204, -v218
	v_fma_f32 v18, v18, v204, -v218
	v_fma_f32 v19, v19, v204, -v218
	v_fma_f32 v20, v20, v204, -v218
	v_fma_f32 v21, v21, v204, -v218
	v_fma_f32 v22, v22, v204, -v218
	v_fma_f32 v23, v23, v204, -v218
	v_exp_f32_e32 v16, v16
	v_exp_f32_e32 v17, v17
	v_exp_f32_e32 v18, v18
	v_exp_f32_e32 v19, v19
	v_exp_f32_e32 v20, v20
	v_exp_f32_e32 v21, v21
	v_exp_f32_e32 v22, v22
	v_exp_f32_e32 v23, v23
	v_mov_b32_e32 v165, v16
	v_mov_b32_e32 v166, v17
	v_mov_b32_e32 v167, v18
	v_mov_b32_e32 v134, v19
	v_add_f32_e32 v165, v165, v20
	v_add_f32_e32 v166, v166, v21
	v_add_f32_e32 v167, v167, v22
	v_add_f32_e32 v134, v134, v23
	v_cvt_pk_bf16_f32 v184, v16, v17
	v_cvt_pk_bf16_f32 v185, v18, v19
	v_cvt_pk_bf16_f32 v186, v20, v21
	v_cvt_pk_bf16_f32 v187, v22, v23
	v_fma_f32 v24, v24, v204, -v218
	v_fma_f32 v25, v25, v204, -v218
	v_fma_f32 v26, v26, v204, -v218
	v_fma_f32 v27, v27, v204, -v218
	v_fma_f32 v28, v28, v204, -v218
	v_fma_f32 v29, v29, v204, -v218
	v_fma_f32 v30, v30, v204, -v218
	v_fma_f32 v31, v31, v204, -v218
	v_exp_f32_e32 v24, v24
	v_exp_f32_e32 v25, v25
	v_exp_f32_e32 v26, v26
	v_exp_f32_e32 v27, v27
	v_exp_f32_e32 v28, v28
	v_exp_f32_e32 v29, v29
	v_exp_f32_e32 v30, v30
	v_exp_f32_e32 v31, v31
	v_add_f32_e32 v165, v165, v24
	v_add_f32_e32 v166, v166, v25
	v_add_f32_e32 v167, v167, v26
	v_add_f32_e32 v134, v134, v27
	v_add_f32_e32 v165, v165, v28
	v_add_f32_e32 v166, v166, v29
	v_add_f32_e32 v167, v167, v30
	v_add_f32_e32 v134, v134, v31
	v_cvt_pk_bf16_f32 v188, v24, v25
	v_cvt_pk_bf16_f32 v189, v26, v27
	v_cvt_pk_bf16_f32 v190, v28, v29
	v_cvt_pk_bf16_f32 v191, v30, v31
	v_fma_f32 v32, v32, v204, -v218
	v_fma_f32 v33, v33, v204, -v218
	v_fma_f32 v34, v34, v204, -v218
	v_fma_f32 v35, v35, v204, -v218
	v_fma_f32 v36, v36, v204, -v218
	v_fma_f32 v37, v37, v204, -v218
	v_fma_f32 v38, v38, v204, -v218
	v_fma_f32 v39, v39, v204, -v218
	v_exp_f32_e32 v32, v32
	v_exp_f32_e32 v33, v33
	v_exp_f32_e32 v34, v34
	v_exp_f32_e32 v35, v35
	v_exp_f32_e32 v36, v36
	v_exp_f32_e32 v37, v37
	v_exp_f32_e32 v38, v38
	v_exp_f32_e32 v39, v39
	v_add_f32_e32 v165, v165, v32
	v_add_f32_e32 v166, v166, v33
	v_add_f32_e32 v167, v167, v34
	v_add_f32_e32 v134, v134, v35
	v_add_f32_e32 v165, v165, v36
	v_add_f32_e32 v166, v166, v37
	v_add_f32_e32 v167, v167, v38
	v_add_f32_e32 v134, v134, v39
	v_cvt_pk_bf16_f32 v32, v32, v33
	v_cvt_pk_bf16_f32 v33, v34, v35
	v_cvt_pk_bf16_f32 v34, v36, v37
	v_cvt_pk_bf16_f32 v35, v38, v39
	v_fma_f32 v40, v40, v204, -v218
	v_fma_f32 v41, v41, v204, -v218
	v_fma_f32 v42, v42, v204, -v218
	v_fma_f32 v43, v43, v204, -v218
	v_fma_f32 v44, v44, v204, -v218
	v_fma_f32 v45, v45, v204, -v218
	v_fma_f32 v46, v46, v204, -v218
	v_fma_f32 v47, v47, v204, -v218
	v_exp_f32_e32 v40, v40
	v_exp_f32_e32 v41, v41
	v_exp_f32_e32 v42, v42
	v_exp_f32_e32 v43, v43
	v_exp_f32_e32 v44, v44
	v_exp_f32_e32 v45, v45
	v_exp_f32_e32 v46, v46
	v_exp_f32_e32 v47, v47
	v_add_f32_e32 v165, v165, v40
	v_add_f32_e32 v166, v166, v41
	v_add_f32_e32 v167, v167, v42
	v_add_f32_e32 v134, v134, v43
	v_add_f32_e32 v165, v165, v44
	v_add_f32_e32 v166, v166, v45
	v_add_f32_e32 v167, v167, v46
	v_add_f32_e32 v134, v134, v47
	v_cvt_pk_bf16_f32 v36, v40, v41
	v_cvt_pk_bf16_f32 v37, v42, v43
	v_cvt_pk_bf16_f32 v38, v44, v45
	v_cvt_pk_bf16_f32 v39, v46, v47
	ds_read_b64_tr_b16 v[40:41], v202 offset:30720
	ds_read_b64_tr_b16 v[42:43], v202 offset:32256
	ds_read_b64_tr_b16 v[44:45], v202 offset:30784
	ds_read_b64_tr_b16 v[46:47], v202 offset:32320
	s_waitcnt lgkmcnt(6)
	v_mfma_f32_32x32x16_bf16 v[0:15], v[236:239], v[32:35], 0
	v_fma_f32 v48, v48, v204, -v218
	v_fma_f32 v49, v49, v204, -v218
	v_fma_f32 v50, v50, v204, -v218
	v_fma_f32 v51, v51, v204, -v218
	v_fma_f32 v52, v52, v204, -v218
	v_fma_f32 v53, v53, v204, -v218
	v_fma_f32 v54, v54, v204, -v218
	v_fma_f32 v55, v55, v204, -v218
	v_exp_f32_e32 v48, v48
	v_exp_f32_e32 v49, v49
	v_exp_f32_e32 v50, v50
	v_exp_f32_e32 v51, v51
	v_exp_f32_e32 v52, v52
	v_exp_f32_e32 v53, v53
	s_waitcnt lgkmcnt(4)
	v_mfma_f32_32x32x16_bf16 v[16:31], v[248:251], v[32:35], 0
	v_exp_f32_e32 v54, v54
	v_exp_f32_e32 v55, v55
	v_add_f32_e32 v165, v165, v48
	v_add_f32_e32 v166, v166, v49
	v_add_f32_e32 v167, v167, v50
	v_add_f32_e32 v134, v134, v51
	v_add_f32_e32 v165, v165, v52
	v_add_f32_e32 v166, v166, v53
	v_add_f32_e32 v167, v167, v54
	v_add_f32_e32 v134, v134, v55
	v_cvt_pk_bf16_f32 v48, v48, v49
	v_cvt_pk_bf16_f32 v49, v50, v51
	v_cvt_pk_bf16_f32 v50, v52, v53
	v_cvt_pk_bf16_f32 v51, v54, v55
	ds_read_b64_tr_b16 v[236:237], v202 offset:33792
	ds_read_b64_tr_b16 v[238:239], v202 offset:35328
	ds_read_b64_tr_b16 v[248:249], v202 offset:33856
	ds_read_b64_tr_b16 v[250:251], v202 offset:35392
	s_waitcnt lgkmcnt(6)
	v_mfma_f32_32x32x16_bf16 v[0:15], v[40:43], v[36:39], v[0:15]
	v_fma_f32 v56, v56, v204, -v218
	v_fma_f32 v57, v57, v204, -v218
	v_fma_f32 v58, v58, v204, -v218
	v_fma_f32 v59, v59, v204, -v218
	v_fma_f32 v60, v60, v204, -v218
	v_fma_f32 v61, v61, v204, -v218
	v_fma_f32 v62, v62, v204, -v218
	v_fma_f32 v63, v63, v204, -v218
	v_exp_f32_e32 v56, v56
	v_exp_f32_e32 v57, v57
	v_exp_f32_e32 v58, v58
	v_exp_f32_e32 v59, v59
	v_exp_f32_e32 v60, v60
	v_exp_f32_e32 v61, v61
	s_waitcnt lgkmcnt(4)
	v_mfma_f32_32x32x16_bf16 v[16:31], v[44:47], v[36:39], v[16:31]
	v_exp_f32_e32 v62, v62
	v_exp_f32_e32 v63, v63
	v_add_f32_e32 v165, v165, v56
	v_add_f32_e32 v166, v166, v57
	v_add_f32_e32 v167, v167, v58
	v_add_f32_e32 v134, v134, v59
	v_add_f32_e32 v165, v165, v60
	v_add_f32_e32 v166, v166, v61
	v_add_f32_e32 v167, v167, v62
	v_add_f32_e32 v134, v134, v63
	v_cvt_pk_bf16_f32 v52, v56, v57
	v_cvt_pk_bf16_f32 v53, v58, v59
	v_cvt_pk_bf16_f32 v54, v60, v61
	v_cvt_pk_bf16_f32 v55, v62, v63
	ds_read_b64_tr_b16 v[40:41], v202 offset:36864
	ds_read_b64_tr_b16 v[42:43], v202 offset:38400
	ds_read_b64_tr_b16 v[44:45], v202 offset:36928
	ds_read_b64_tr_b16 v[46:47], v202 offset:38464
	ds_read_b64_tr_b16 v[56:57], v202 offset:39936
	ds_read_b64_tr_b16 v[58:59], v202 offset:41472
	ds_read_b64_tr_b16 v[60:61], v202 offset:40000
	ds_read_b64_tr_b16 v[62:63], v202 offset:41536
	s_waitcnt lgkmcnt(10)
	v_mfma_f32_32x32x16_bf16 v[0:15], v[236:239], v[48:51], v[0:15]
	v_fma_f32 v64, v64, v204, -v218
	v_fma_f32 v65, v65, v204, -v218
	v_fma_f32 v66, v66, v204, -v218
	v_fma_f32 v67, v67, v204, -v218
	v_fma_f32 v68, v68, v204, -v218
	v_fma_f32 v69, v69, v204, -v218
	v_fma_f32 v70, v70, v204, -v218
	v_fma_f32 v71, v71, v204, -v218
	v_exp_f32_e32 v64, v64
	v_exp_f32_e32 v65, v65
	v_exp_f32_e32 v66, v66
	v_exp_f32_e32 v67, v67
	v_exp_f32_e32 v68, v68
	v_exp_f32_e32 v69, v69
	s_waitcnt lgkmcnt(8)
	v_mfma_f32_32x32x16_bf16 v[16:31], v[248:251], v[48:51], v[16:31]
	v_exp_f32_e32 v70, v70
	v_exp_f32_e32 v71, v71
	v_add_f32_e32 v165, v165, v64
	v_add_f32_e32 v166, v166, v65
	v_add_f32_e32 v167, v167, v66
	v_add_f32_e32 v134, v134, v67
	v_add_f32_e32 v165, v165, v68
	v_add_f32_e32 v166, v166, v69
	v_add_f32_e32 v167, v167, v70
	v_add_f32_e32 v134, v134, v71
	v_cvt_pk_bf16_f32 v64, v64, v65
	v_cvt_pk_bf16_f32 v65, v66, v67
	v_cvt_pk_bf16_f32 v66, v68, v69
	v_cvt_pk_bf16_f32 v67, v70, v71
	ds_read_b64_tr_b16 v[236:237], v202 offset:43008
	ds_read_b64_tr_b16 v[238:239], v202 offset:44544
	ds_read_b64_tr_b16 v[248:249], v202 offset:43072
	ds_read_b64_tr_b16 v[250:251], v202 offset:44608
	s_waitcnt lgkmcnt(10)
	v_mfma_f32_32x32x16_bf16 v[0:15], v[40:43], v[52:55], v[0:15]
	v_fma_f32 v72, v72, v204, -v218
	v_fma_f32 v73, v73, v204, -v218
	v_fma_f32 v74, v74, v204, -v218
	v_fma_f32 v75, v75, v204, -v218
	v_fma_f32 v76, v76, v204, -v218
	v_fma_f32 v77, v77, v204, -v218
	v_fma_f32 v78, v78, v204, -v218
	v_fma_f32 v79, v79, v204, -v218
	v_exp_f32_e32 v72, v72
	v_exp_f32_e32 v73, v73
	v_exp_f32_e32 v74, v74
	v_exp_f32_e32 v75, v75
	v_exp_f32_e32 v76, v76
	v_exp_f32_e32 v77, v77
	s_waitcnt lgkmcnt(8)
	v_mfma_f32_32x32x16_bf16 v[16:31], v[44:47], v[52:55], v[16:31]
	v_exp_f32_e32 v78, v78
	v_exp_f32_e32 v79, v79
	v_add_f32_e32 v165, v165, v72
	v_add_f32_e32 v166, v166, v73
	v_add_f32_e32 v167, v167, v74
	v_add_f32_e32 v134, v134, v75
	v_add_f32_e32 v165, v165, v76
	v_add_f32_e32 v166, v166, v77
	v_add_f32_e32 v167, v167, v78
	v_add_f32_e32 v134, v134, v79
	v_cvt_pk_bf16_f32 v68, v72, v73
	v_cvt_pk_bf16_f32 v69, v74, v75
	v_cvt_pk_bf16_f32 v70, v76, v77
	v_cvt_pk_bf16_f32 v71, v78, v79
	ds_read_b64_tr_b16 v[40:41], v202 offset:46080
	ds_read_b64_tr_b16 v[42:43], v202 offset:47616
	ds_read_b64_tr_b16 v[44:45], v202 offset:46144
	ds_read_b64_tr_b16 v[46:47], v202 offset:47680
	s_waitcnt lgkmcnt(10)
	v_mfma_f32_32x32x16_bf16 v[0:15], v[56:59], v[64:67], v[0:15]
	v_fma_f32 v168, v168, v204, -v218
	v_fma_f32 v169, v169, v204, -v218
	v_fma_f32 v170, v170, v204, -v218
	v_fma_f32 v171, v171, v204, -v218
	v_fma_f32 v172, v172, v204, -v218
	v_fma_f32 v173, v173, v204, -v218
	v_fma_f32 v174, v174, v204, -v218
	v_fma_f32 v175, v175, v204, -v218
	v_exp_f32_e32 v168, v168
	v_exp_f32_e32 v169, v169
	v_exp_f32_e32 v170, v170
	v_exp_f32_e32 v171, v171
	v_exp_f32_e32 v172, v172
	v_exp_f32_e32 v173, v173
	s_waitcnt lgkmcnt(8)
	v_mfma_f32_32x32x16_bf16 v[16:31], v[60:63], v[64:67], v[16:31]
	v_exp_f32_e32 v174, v174
	v_exp_f32_e32 v175, v175
	v_add_f32_e32 v165, v165, v168
	v_add_f32_e32 v166, v166, v169
	v_add_f32_e32 v167, v167, v170
	v_add_f32_e32 v134, v134, v171
	v_add_f32_e32 v165, v165, v172
	v_add_f32_e32 v166, v166, v173
	v_add_f32_e32 v167, v167, v174
	v_add_f32_e32 v134, v134, v175
	v_cvt_pk_bf16_f32 v168, v168, v169
	v_cvt_pk_bf16_f32 v169, v170, v171
	v_cvt_pk_bf16_f32 v170, v172, v173
	v_cvt_pk_bf16_f32 v171, v174, v175
	ds_read_b64_tr_b16 v[56:57], v202 offset:49152
	ds_read_b64_tr_b16 v[58:59], v202 offset:50688
	ds_read_b64_tr_b16 v[60:61], v202 offset:49216
	ds_read_b64_tr_b16 v[62:63], v202 offset:50752
	s_waitcnt lgkmcnt(10)
	v_mfma_f32_32x32x16_bf16 v[0:15], v[236:239], v[68:71], v[0:15]
	v_fma_f32 v176, v176, v204, -v218
	v_fma_f32 v177, v177, v204, -v218
	v_fma_f32 v178, v178, v204, -v218
	v_fma_f32 v179, v179, v204, -v218
	v_fma_f32 v180, v180, v204, -v218
	v_fma_f32 v181, v181, v204, -v218
	v_fma_f32 v182, v182, v204, -v218
	v_fma_f32 v183, v183, v204, -v218
	v_exp_f32_e32 v176, v176
	v_exp_f32_e32 v177, v177
	v_exp_f32_e32 v178, v178
	v_exp_f32_e32 v179, v179
	v_exp_f32_e32 v180, v180
	v_exp_f32_e32 v181, v181
	s_waitcnt lgkmcnt(8)
	v_mfma_f32_32x32x16_bf16 v[16:31], v[248:251], v[68:71], v[16:31]
	v_exp_f32_e32 v182, v182
	v_exp_f32_e32 v183, v183
	v_add_f32_e32 v165, v165, v176
	v_add_f32_e32 v166, v166, v177
	v_add_f32_e32 v167, v167, v178
	v_add_f32_e32 v134, v134, v179
	v_add_f32_e32 v165, v165, v180
	v_add_f32_e32 v166, v166, v181
	v_add_f32_e32 v167, v167, v182
	v_add_f32_e32 v134, v134, v183
	v_cvt_pk_bf16_f32 v172, v176, v177
	v_cvt_pk_bf16_f32 v173, v178, v179
	v_cvt_pk_bf16_f32 v174, v180, v181
	v_cvt_pk_bf16_f32 v175, v182, v183
	ds_read_b64_tr_b16 v[236:237], v202 offset:52224
	ds_read_b64_tr_b16 v[238:239], v202 offset:53760
	ds_read_b64_tr_b16 v[248:249], v202 offset:52288
	ds_read_b64_tr_b16 v[250:251], v202 offset:53824
	s_waitcnt lgkmcnt(10)
	v_mfma_f32_32x32x16_bf16 v[0:15], v[40:43], v[168:171], v[0:15]
	v_fma_f32 v220, v220, v204, -v218
	v_fma_f32 v221, v221, v204, -v218
	v_fma_f32 v222, v222, v204, -v218
	v_fma_f32 v223, v223, v204, -v218
	v_fma_f32 v224, v224, v204, -v218
	v_fma_f32 v225, v225, v204, -v218
	v_fma_f32 v226, v226, v204, -v218
	v_fma_f32 v227, v227, v204, -v218
	v_exp_f32_e32 v220, v220
	v_exp_f32_e32 v221, v221
	v_exp_f32_e32 v222, v222
	v_exp_f32_e32 v223, v223
	v_exp_f32_e32 v224, v224
	v_exp_f32_e32 v225, v225
	s_waitcnt lgkmcnt(8)
	v_mfma_f32_32x32x16_bf16 v[16:31], v[44:47], v[168:171], v[16:31]
	v_exp_f32_e32 v226, v226
	v_exp_f32_e32 v227, v227
	v_add_f32_e32 v165, v165, v220
	v_add_f32_e32 v166, v166, v221
	v_add_f32_e32 v167, v167, v222
	v_add_f32_e32 v134, v134, v223
	v_add_f32_e32 v165, v165, v224
	v_add_f32_e32 v166, v166, v225
	v_add_f32_e32 v167, v167, v226
	v_add_f32_e32 v134, v134, v227
	v_cvt_pk_bf16_f32 v220, v220, v221
	v_cvt_pk_bf16_f32 v221, v222, v223
	v_cvt_pk_bf16_f32 v222, v224, v225
	v_cvt_pk_bf16_f32 v223, v226, v227
	ds_read_b64_tr_b16 v[40:41], v202 offset:55296
	ds_read_b64_tr_b16 v[42:43], v202 offset:56832
	ds_read_b64_tr_b16 v[44:45], v202 offset:55360
	ds_read_b64_tr_b16 v[46:47], v202 offset:56896
	s_waitcnt lgkmcnt(10)
	v_mfma_f32_32x32x16_bf16 v[0:15], v[56:59], v[172:175], v[0:15]
	v_fma_f32 v228, v228, v204, -v218
	v_fma_f32 v229, v229, v204, -v218
	v_fma_f32 v230, v230, v204, -v218
	v_fma_f32 v231, v231, v204, -v218
	v_fma_f32 v232, v232, v204, -v218
	v_fma_f32 v233, v233, v204, -v218
	v_fma_f32 v234, v234, v204, -v218
	v_fma_f32 v235, v235, v204, -v218
	v_exp_f32_e32 v228, v228
	v_exp_f32_e32 v229, v229
	v_exp_f32_e32 v230, v230
	v_exp_f32_e32 v231, v231
	v_exp_f32_e32 v232, v232
	v_exp_f32_e32 v233, v233
	s_waitcnt lgkmcnt(8)
	v_mfma_f32_32x32x16_bf16 v[16:31], v[60:63], v[172:175], v[16:31]
	v_exp_f32_e32 v234, v234
	v_exp_f32_e32 v235, v235
	v_add_f32_e32 v165, v165, v228
	v_add_f32_e32 v166, v166, v229
	v_add_f32_e32 v167, v167, v230
	v_add_f32_e32 v134, v134, v231
	v_add_f32_e32 v165, v165, v232
	v_add_f32_e32 v166, v166, v233
	v_add_f32_e32 v167, v167, v234
	v_add_f32_e32 v134, v134, v235
	v_cvt_pk_bf16_f32 v224, v228, v229
	v_cvt_pk_bf16_f32 v225, v230, v231
	v_cvt_pk_bf16_f32 v226, v232, v233
	v_cvt_pk_bf16_f32 v227, v234, v235
	ds_read_b64_tr_b16 v[56:57], v202 offset:58368
	ds_read_b64_tr_b16 v[58:59], v202 offset:59904
	ds_read_b64_tr_b16 v[60:61], v202 offset:58432
	ds_read_b64_tr_b16 v[62:63], v202 offset:59968
	s_waitcnt lgkmcnt(10)
	v_mfma_f32_32x32x16_bf16 v[0:15], v[236:239], v[220:223], v[0:15]
	s_waitcnt lgkmcnt(8)
	v_mfma_f32_32x32x16_bf16 v[16:31], v[248:251], v[220:223], v[16:31]
	ds_read_b64_tr_b16 v[236:237], v202 offset:61440
	ds_read_b64_tr_b16 v[238:239], v202 offset:62976
	ds_read_b64_tr_b16 v[248:249], v202 offset:61504
	ds_read_b64_tr_b16 v[250:251], v202 offset:63040
	s_waitcnt lgkmcnt(10)
	v_mfma_f32_32x32x16_bf16 v[0:15], v[40:43], v[224:227], v[0:15]
	s_waitcnt lgkmcnt(8)
	v_mfma_f32_32x32x16_bf16 v[16:31], v[44:47], v[224:227], v[16:31]
	s_waitcnt lgkmcnt(6)
	v_mfma_f32_32x32x16_bf16 v[0:15], v[56:59], v[184:187], v[0:15]
	s_waitcnt lgkmcnt(4)
	v_mfma_f32_32x32x16_bf16 v[16:31], v[60:63], v[184:187], v[16:31]
	s_waitcnt lgkmcnt(2)
	v_mfma_f32_32x32x16_bf16 v[0:15], v[236:239], v[188:191], v[0:15]
	s_waitcnt lgkmcnt(0)
	v_mfma_f32_32x32x16_bf16 v[16:31], v[248:251], v[188:191], v[16:31]
	v_add_f32_e32 v165, v165, v166
	v_add_f32_e32 v167, v167, v134
	v_xor_b32_e32 v205, 32, v197
	v_lshlrev_b32_e32 v205, 2, v205
	v_mov_b32_e32 v72, v218
	v_add_f32_e32 v74, v165, v167
	ds_bpermute_b32 v32, v205, v74
	s_branch .LBB0_431

.LBB0_968:
	s_and_b32 s30, s3, 3
	v_lshlrev_b32_e32 v2, 3, v8
	v_and_b32_e32 v5, 56, v2
	v_ashrrev_i32_e32 v2, 3, v8
	s_lshl_b32 s3, s30, 6
	s_mov_b64 s[4:5], -1
	s_and_b64 vcc, exec, s[22:23]
	s_cbranch_vccz .LBB0_970
	v_ashrrev_i32_e32 v3, 31, v2
	v_lshlrev_b64 v[10:11], 8, v[2:3]
	s_ashr_i32 s19, s18, 31
	v_lshl_add_u64 v[10:11], v[10:11], 0, s[10:11]
	s_lshl_b64 s[4:5], s[18:19], 16
	v_or_b32_e32 v10, v10, v5
	v_lshl_add_u64 v[10:11], v[10:11], 0, s[4:5]
	v_or_b32_e32 v10, s3, v10
	v_readlane_b32 s56, v253, 42
	v_lshlrev_b64 v[18:19], 2, v[10:11]
	v_readlane_b32 s68, v253, 54
	v_readlane_b32 s69, v253, 55
	v_readlane_b32 s70, v253, 56
	v_readlane_b32 s71, v253, 57
	v_lshl_add_u64 v[14:15], s[68:69], 0, v[18:19]
	global_load_dwordx4 v[20:23], v[14:15], off offset:16
	global_load_dwordx4 v[24:27], v[14:15], off
	v_readlane_b32 s64, v253, 50
	v_readlane_b32 s66, v253, 52
	v_readlane_b32 s57, v253, 43
	v_readlane_b32 s58, v253, 44
	v_readlane_b32 s59, v253, 45
	v_readlane_b32 s60, v253, 46
	v_readlane_b32 s61, v253, 47
	v_readlane_b32 s62, v253, 48
	v_readlane_b32 s63, v253, 49
	v_readlane_b32 s65, v253, 51
	v_readlane_b32 s67, v253, 53
	s_mov_b32 s66, 0x3a800000
	s_mov_b32 s64, s90
	s_mov_b64 s[4:5], 0
	v_lshl_add_u64 v[14:15], s[70:71], 0, v[18:19]
	global_load_dwordx4 v[28:31], v[14:15], off offset:16
	global_load_dwordx4 v[32:35], v[14:15], off
	s_mov_b64 s[70:71], s[84:85]

.LBB0_972:
	v_add_u32_e32 v2, 0x200, v8
	v_ashrrev_i32_e32 v4, 3, v2
	v_cndmask_b32_e64 v2, 0, 1, s[22:23]
	s_mov_b64 s[24:25], -1
	v_cmp_ne_u32_e64 s[4:5], 1, v2
	s_andn2_b64 vcc, exec, s[22:23]
	v_or_b32_e32 v2, s10, v5
	s_cbranch_vccnz .LBB0_974
	v_ashrrev_i32_e32 v5, 31, v4
	s_ashr_i32 s19, s18, 31
	v_lshlrev_b64 v[10:11], 8, v[4:5]
	v_mov_b32_e32 v3, v195
	s_lshl_b64 s[22:23], s[18:19], 16
	v_lshl_add_u64 v[10:11], v[2:3], 0, v[10:11]
	v_lshl_add_u64 v[10:11], v[10:11], 0, s[22:23]
	v_or_b32_e32 v10, s3, v10
	v_readlane_b32 s56, v253, 42
	v_lshlrev_b64 v[18:19], 2, v[10:11]
	v_readlane_b32 s68, v253, 54
	v_readlane_b32 s69, v253, 55
	v_readlane_b32 s70, v253, 56
	v_readlane_b32 s71, v253, 57
	v_lshl_add_u64 v[14:15], s[68:69], 0, v[18:19]
	global_load_dwordx4 v[36:39], v[14:15], off offset:16
	global_load_dwordx4 v[40:43], v[14:15], off
	v_readlane_b32 s64, v253, 50
	v_readlane_b32 s66, v253, 52
	s_mov_b32 s66, 0x3a800000
	s_mov_b32 s64, s90
	s_mov_b64 s[24:25], 0
	v_readlane_b32 s57, v253, 43
	v_readlane_b32 s58, v253, 44
	v_readlane_b32 s59, v253, 45
	v_readlane_b32 s60, v253, 46
	v_readlane_b32 s61, v253, 47
	v_readlane_b32 s62, v253, 48
	v_readlane_b32 s63, v253, 49
	v_readlane_b32 s65, v253, 51
	v_readlane_b32 s67, v253, 53
	v_lshl_add_u64 v[14:15], s[70:71], 0, v[18:19]
	global_load_dwordx4 v[44:47], v[14:15], off offset:16
	global_load_dwordx4 v[48:51], v[14:15], off
	s_mov_b64 s[70:71], s[84:85]

.LBB0_976:
	v_add_u32_e32 v3, 0x400, v8
	v_ashrrev_i32_e32 v4, 3, v3
	s_and_b64 vcc, exec, s[4:5]
	s_mov_b64 s[22:23], -1
	s_cbranch_vccnz .LBB0_978
	v_ashrrev_i32_e32 v5, 31, v4
	s_ashr_i32 s19, s18, 31
	v_lshlrev_b64 v[10:11], 8, v[4:5]
	v_mov_b32_e32 v3, v195
	s_lshl_b64 s[22:23], s[18:19], 16
	v_lshl_add_u64 v[10:11], v[2:3], 0, v[10:11]
	v_lshl_add_u64 v[10:11], v[10:11], 0, s[22:23]
	v_or_b32_e32 v10, s3, v10
	v_readlane_b32 s56, v253, 42
	v_lshlrev_b64 v[18:19], 2, v[10:11]
	v_readlane_b32 s68, v253, 54
	v_readlane_b32 s69, v253, 55
	v_readlane_b32 s70, v253, 56
	v_readlane_b32 s71, v253, 57
	v_lshl_add_u64 v[14:15], s[68:69], 0, v[18:19]
	global_load_dwordx4 v[52:55], v[14:15], off offset:16
	global_load_dwordx4 v[56:59], v[14:15], off
	v_readlane_b32 s64, v253, 50
	v_readlane_b32 s66, v253, 52
	s_mov_b32 s66, 0x3a800000
	s_mov_b32 s64, s90
	s_mov_b64 s[22:23], 0
	v_readlane_b32 s57, v253, 43
	v_readlane_b32 s58, v253, 44
	v_readlane_b32 s59, v253, 45
	v_readlane_b32 s60, v253, 46
	v_readlane_b32 s61, v253, 47
	v_readlane_b32 s62, v253, 48
	v_readlane_b32 s63, v253, 49
	v_readlane_b32 s65, v253, 51
	v_readlane_b32 s67, v253, 53
	v_lshl_add_u64 v[14:15], s[70:71], 0, v[18:19]
	global_load_dwordx4 v[60:63], v[14:15], off offset:16
	global_load_dwordx4 v[64:67], v[14:15], off
	s_mov_b64 s[70:71], s[84:85]

.LBB0_980:
	v_add_u32_e32 v3, 0x600, v8
	v_ashrrev_i32_e32 v4, 3, v3
	s_and_b64 vcc, exec, s[4:5]
	s_mov_b64 s[4:5], -1
	s_cbranch_vccnz .LBB0_982
	v_ashrrev_i32_e32 v5, 31, v4
	s_ashr_i32 s19, s18, 31
	v_lshlrev_b64 v[8:9], 8, v[4:5]
	v_mov_b32_e32 v3, v195
	s_lshl_b64 s[4:5], s[18:19], 16
	v_lshl_add_u64 v[2:3], v[2:3], 0, v[8:9]
	v_lshl_add_u64 v[2:3], v[2:3], 0, s[4:5]
	v_or_b32_e32 v2, s3, v2
	v_readlane_b32 s56, v253, 42
	v_lshlrev_b64 v[2:3], 2, v[2:3]
	v_readlane_b32 s68, v253, 54
	v_readlane_b32 s69, v253, 55
	v_readlane_b32 s70, v253, 56
	v_readlane_b32 s71, v253, 57
	v_lshl_add_u64 v[12:13], s[68:69], 0, v[2:3]
	global_load_dwordx4 v[68:71], v[12:13], off offset:16
	global_load_dwordx4 v[72:75], v[12:13], off
	v_lshl_add_u64 v[2:3], s[70:71], 0, v[2:3]
	v_readlane_b32 s64, v253, 50
	v_readlane_b32 s66, v253, 52
	s_mov_b32 s66, 0x3a800000
	s_mov_b32 s64, s90
	s_mov_b64 s[70:71], s[84:85]
	s_mov_b64 s[4:5], 0
	v_readlane_b32 s57, v253, 43
	v_readlane_b32 s58, v253, 44
	v_readlane_b32 s59, v253, 45
	v_readlane_b32 s60, v253, 46
	v_readlane_b32 s61, v253, 47
	v_readlane_b32 s62, v253, 48
	v_readlane_b32 s63, v253, 49
	v_readlane_b32 s65, v253, 51
	v_readlane_b32 s67, v253, 53
	global_load_dwordx4 v[76:79], v[2:3], off offset:16
	global_load_dwordx4 v[80:83], v[2:3], off
.LBB0_982:
	s_andn2_b64 vcc, exec, s[4:5]
	s_cbranch_vccnz .Lxa_cvt_tail
	v_lshl_add_u32 v2, s18, 8, v4
	v_ashrrev_i32_e32 v3, 31, v2
	v_lshlrev_b64 v[2:3], 10, v[2:3]
	v_lshl_add_u64 v[2:3], s[8:9], 0, v[2:3]
	s_lshl_b32 s92, s3, 1
	v_lshl_add_u64 v[2:3], v[2:3], 0, s[92:93]
	v_lshl_add_u64 v[2:3], v[2:3], 0, v[194:195]
	global_load_dwordx4 v[136:139], v[2:3], off
	global_load_dwordx4 v[140:143], v[2:3], off offset:512
	s_branch .LBB0_984
.Lxa_cvt_tail:
	s_waitcnt vmcnt(0)
	v_cvt_pk_bf16_f32 v98, v20, v21
	v_cvt_pk_bf16_f32 v96, v24, v25
	v_cvt_pk_bf16_f32 v97, v26, v27
	v_cvt_pk_bf16_f32 v99, v22, v23
	v_cvt_pk_bf16_f32 v102, v28, v29
	v_cvt_pk_bf16_f32 v100, v32, v33
	v_cvt_pk_bf16_f32 v101, v34, v35
	v_cvt_pk_bf16_f32 v103, v30, v31
	v_cvt_pk_bf16_f32 v106, v36, v37
	v_cvt_pk_bf16_f32 v104, v40, v41
	v_cvt_pk_bf16_f32 v105, v42, v43
	v_cvt_pk_bf16_f32 v107, v38, v39
	v_cvt_pk_bf16_f32 v110, v44, v45
	v_cvt_pk_bf16_f32 v108, v48, v49
	v_cvt_pk_bf16_f32 v109, v50, v51
	v_cvt_pk_bf16_f32 v111, v46, v47
	v_cvt_pk_bf16_f32 v114, v52, v53
	v_cvt_pk_bf16_f32 v112, v56, v57
	v_cvt_pk_bf16_f32 v113, v58, v59
	v_cvt_pk_bf16_f32 v115, v54, v55
	v_cvt_pk_bf16_f32 v134, v60, v61
	v_cvt_pk_bf16_f32 v132, v64, v65
	v_cvt_pk_bf16_f32 v133, v66, v67
	v_cvt_pk_bf16_f32 v135, v62, v63
	v_cvt_pk_bf16_f32 v138, v68, v69
	v_cvt_pk_bf16_f32 v136, v72, v73
	v_cvt_pk_bf16_f32 v137, v74, v75
	v_cvt_pk_bf16_f32 v139, v70, v71
	v_cvt_pk_bf16_f32 v142, v76, v77
	v_cvt_pk_bf16_f32 v140, v80, v81
	v_cvt_pk_bf16_f32 v141, v82, v83
	v_cvt_pk_bf16_f32 v143, v78, v79
